# scan producer waves touch the gate tensor z during the second half of the chunk loop (memory-side cache warm-up for the group-norm phase)
# speedup vs baseline: 1.0074x; 1.0033x over previous
; __device__ __forceinline__ void scan_phase(LAS unsigned char* lds, const bf16_t* R, const bf16_t* Kb, const bf16_t* V, const bf16_t* WA, const float* k_k, const float* k_a, bf16_t* Y, int G, int bid, int tid) {
;     ...
;         if (producer1) { CK_LOAD(A, pta, 0); CK_LOAD(B, ptb, 0); CK_P1(A, pta, 0); CK_P1(B, ptb, 0); CK_LOAD(A, pta, 1); CK_LOAD(B, ptb, 1); }
;         f32x4 H[4];
; #pragma unroll
;         for (int kt = 0; kt < 4; ++kt) H[kt] = (f32x4){0.f, 0.f, 0.f, 0.f};
;         __syncthreads();
;         for (int it = 0; it <= NCH; ++it) {
;             if (producer1 && it + 1 < NCH) { CK_P1(A, pta, it + 1); CK_P1(B, ptb, it + 1); if (it + 2 < NCH) { CK_LOAD(A, pta, it + 2); CK_LOAD(B, ptb, it + 2); } }
.LBB0_918:
	s_andn2_b64 vcc, exec, s[0:1]
	s_cbranch_vccnz .LBB0_921
	s_waitcnt vmcnt(0)
	v_mov_b64_e32 v[134:135], v[188:189]
	v_mov_b64_e32 v[136:137], v[190:191]
	v_mov_b64_e32 v[138:139], v[192:193]
	v_mov_b64_e32 v[140:141], v[194:195]
	v_mov_b32_e32 v187, v196
	v_mov_b64_e32 v[126:127], v[198:199]
	v_mov_b64_e32 v[128:129], v[200:201]
	v_mov_b64_e32 v[130:131], v[202:203]
	v_mov_b64_e32 v[132:133], v[204:205]
	v_mov_b32_e32 v186, v197
	s_cmp_eq_u32 s60, 0x7e8000
	s_cbranch_scc1 .Lmy_p1_noload
	v_lshl_add_u64 v[2:3], v[146:147], 0, s[60:61]
	v_add_co_u32_e32 v28, vcc, 0x18000, v2
	s_nop 1
	v_addc_co_u32_e32 v29, vcc, 0, v3, vcc
	global_load_dwordx2 v[188:189], v[28:29], off
	v_lshl_add_u64 v[28:29], v[148:149], 0, s[60:61]
	v_add_co_u32_e32 v30, vcc, 0x16018000, v28
	s_nop 1
	v_addc_co_u32_e32 v31, vcc, 0, v29, vcc
	global_load_dwordx2 v[190:191], v[30:31], off
	v_add_co_u32_e32 v30, vcc, 0xffff8000, v144
	s_nop 1
	v_addc_co_u32_e32 v31, vcc, -1, v145, vcc
	global_load_dwordx2 v[192:193], v[30:31], off offset:-2048
	global_load_dwordx2 v[194:195], v[30:31], off
	v_lshl_add_u64 v[30:31], v[150:151], 0, s[60:61]
	v_add_co_u32_e32 v32, vcc, 0x4018000, v30
	s_nop 1
	v_addc_co_u32_e32 v33, vcc, 0, v31, vcc
	v_add_co_u32_e32 v2, vcc, 0x1c000, v2
	s_nop 1
	v_addc_co_u32_e32 v3, vcc, 0, v3, vcc
	global_load_dword v196, v[32:33], off
	global_load_dwordx2 v[198:199], v[2:3], off
	v_add_co_u32_e32 v2, vcc, 0x1601c000, v28
	s_nop 1
	v_addc_co_u32_e32 v3, vcc, 0, v29, vcc
	global_load_dwordx2 v[200:201], v[2:3], off
	global_load_dwordx2 v[202:203], v[144:145], off offset:-2048
	global_load_dwordx2 v[204:205], v[144:145], off
	v_add_co_u32_e32 v2, vcc, 0x401c000, v30
	s_nop 1
	v_addc_co_u32_e32 v3, vcc, 0, v31, vcc
	global_load_dword v197, v[2:3], off
	s_and_b32 s98, s62, 0x83
	s_cmp_eq_u32 s98, 0x80
	s_cbranch_scc0 .Lmy_ztouch_skip
	s_lshr_b32 s98, s62, 2
	s_and_b32 s98, s98, 31
	s_lshl_b32 s98, s98, 8
	s_add_i32 s98, s98, s84
	s_lshl_b32 s98, s98, 13
	v_mbcnt_lo_u32_b32 v2, -1, 0
	v_mbcnt_hi_u32_b32 v2, -1, v2
	v_lshl_add_u32 v2, v2, 7, s98
	v_add_u32_e32 v2, 0x1800000, v2
	v_mov_b32_e32 v3, 0
	v_lshl_add_u64 v[2:3], s[100:101], 0, v[2:3]
	global_load_dword v252, v[2:3], off
	s_nop 1
.Lmy_ztouch_skip:
.Lmy_p1_noload:
	v_lshlrev_b32_e32 v2, 16, v134
	v_and_b32_e32 v3, 0xffff0000, v134
	v_lshlrev_b32_e32 v36, 16, v135
	v_and_b32_e32 v37, 0xffff0000, v135
	v_pk_mul_f32 v[44:45], v[8:9], v[2:3]
	v_pk_mul_f32 v[46:47], v[10:11], v[36:37]
	v_pk_mul_f32 v[48:49], v[44:45], v[44:45]
	v_pk_mul_f32 v[38:39], v[46:47], v[46:47]
	v_lshlrev_b32_e32 v40, 16, v140
	v_and_b32_e32 v41, 0xffff0000, v140
	v_lshlrev_b32_e32 v42, 16, v141
	v_and_b32_e32 v43, 0xffff0000, v141
	v_pk_mov_b32 v[50:51], v[48:49], v[38:39] op_sel:[1,0]
	v_mov_b32_e32 v49, v39
	s_andn2_b32 s0, 1, s62
	v_pk_add_f32 v[48:49], v[50:51], v[48:49]
	s_mul_i32 s1, s0, 0x4400
	v_pk_add_f32 v[38:39], v[42:43], -1.0 op_sel_hi:[1,0]
	v_pk_add_f32 v[50:51], v[40:41], -1.0 op_sel_hi:[1,0]
	s_add_i32 s1, s1, 0
	v_pk_fma_f32 v[50:51], v[4:5], v[50:51], 1.0 op_sel_hi:[1,1,0]
	v_pk_fma_f32 v[38:39], v[6:7], v[38:39], 1.0 op_sel_hi:[1,1,0]
	s_mulk_i32 s0, 0xcc00
	v_add_u32_e32 v1, s1, v99
	v_pk_mul_f32 v[38:39], v[38:39], v[36:37]
	v_pk_mul_f32 v[36:37], v[50:51], v[2:3]
	v_add_u32_e32 v2, s1, v103
	s_add_i32 s0, s1, s0
	v_lshlrev_b32_e32 v28, 16, v138
	v_and_b32_e32 v29, 0xffff0000, v138
	v_lshlrev_b32_e32 v30, 16, v139
	v_and_b32_e32 v31, 0xffff0000, v139
	v_lshlrev_b32_e32 v32, 16, v136
	v_and_b32_e32 v33, 0xffff0000, v136
	v_lshlrev_b32_e32 v34, 16, v137
	v_and_b32_e32 v35, 0xffff0000, v137
	ds_write_b128 v1, v[36:39] offset:53248
	ds_write_b128 v1, v[32:35] offset:57344
	v_pk_mul_f32 v[218:219], v[32:33], v[36:37]
	v_pk_mul_f32 v[220:221], v[34:35], v[38:39]
	v_pk_mul_f32 v[218:219], v[218:219], v[208:209]
	v_pk_mul_f32 v[220:221], v[220:221], v[210:211]
	v_pk_add_f32 v[218:219], v[218:219], v[220:221]
	s_nop 0
	v_add_f32_e32 v218, v218, v219
	s_nop 1
	v_add_f32_dpp v218, v218, v218 quad_perm:[1,0,3,2] row_mask:0xf bank_mask:0xf
	s_nop 1
	v_add_f32_dpp v218, v218, v218 quad_perm:[2,3,0,1] row_mask:0xf bank_mask:0xf
	s_nop 1
	v_add_f32_dpp v218, v218, v218 row_half_mirror row_mask:0xf bank_mask:0xf
	s_nop 1
	v_add_f32_dpp v218, v218, v218 row_mirror row_mask:0xf bank_mask:0xf
	s_add_i32 s98, s62, 1
	s_lshl_b32 s98, s98, 10
	v_add_co_u32_e32 v216, vcc, s98, v214
	s_nop 1
	v_addc_co_u32_e32 v217, vcc, 0, v215, vcc
	global_store_dword v[216:217], v218, off
	ds_write_b32 v2, v187 offset:61440
	v_add_u32_e32 v2, s0, v99
	ds_write_b128 v2, v[28:31] offset:31744
	v_lshlrev_b32_e32 v2, 16, v126
	v_and_b32_e32 v3, 0xffff0000, v126
	v_lshlrev_b32_e32 v50, 16, v127
	v_and_b32_e32 v51, 0xffff0000, v127
	v_pk_mul_f32 v[56:57], v[8:9], v[2:3]
	v_pk_mul_f32 v[58:59], v[10:11], v[50:51]
	v_pk_mul_f32 v[36:37], v[56:57], v[56:57]
	v_pk_mul_f32 v[34:35], v[58:59], v[58:59]
	v_lshlrev_b32_e32 v52, 16, v132
	v_pk_mov_b32 v[38:39], v[36:37], v[34:35] op_sel:[1,0]
	v_mov_b32_e32 v37, v35
	v_pk_add_f32 v[34:35], v[38:39], v[36:37]
	v_mov_b32_e32 v37, v48
	v_mov_b32_e32 v36, v34
	v_mov_b32_e32 v48, v35
	v_pk_add_f32 v[34:35], v[36:37], v[48:49]
	v_and_b32_e32 v53, 0xffff0000, v132
	v_lshlrev_b32_e32 v54, 16, v133
	v_mov_b32_dpp v37, v35 quad_perm:[1,0,3,2] row_mask:0xf bank_mask:0xf bound_ctrl:1
	v_mov_b32_dpp v36, v34 quad_perm:[1,0,3,2] row_mask:0xf bank_mask:0xf bound_ctrl:1
	v_pk_add_f32 v[34:35], v[34:35], v[36:37]
	v_and_b32_e32 v55, 0xffff0000, v133
	v_lshlrev_b32_e32 v32, 16, v128
	v_mov_b32_dpp v37, v35 quad_perm:[2,3,0,1] row_mask:0xf bank_mask:0xf bound_ctrl:1
	v_mov_b32_dpp v36, v34 quad_perm:[2,3,0,1] row_mask:0xf bank_mask:0xf bound_ctrl:1
	v_pk_add_f32 v[34:35], v[34:35], v[36:37]
	v_and_b32_e32 v33, 0xffff0000, v128
	v_lshlrev_b32_e32 v28, 16, v130
	v_mov_b32_dpp v37, v35 row_half_mirror row_mask:0xf bank_mask:0xf bound_ctrl:1
	v_mov_b32_dpp v36, v34 row_half_mirror row_mask:0xf bank_mask:0xf bound_ctrl:1
	v_pk_add_f32 v[34:35], v[34:35], v[36:37]
	v_and_b32_e32 v29, 0xffff0000, v130
	v_lshlrev_b32_e32 v30, 16, v131
	v_mov_b32_dpp v37, v35 row_mirror row_mask:0xf bank_mask:0xf bound_ctrl:1
	v_mov_b32_dpp v36, v34 row_mirror row_mask:0xf bank_mask:0xf bound_ctrl:1
	v_pk_add_f32 v[48:49], v[34:35], v[36:37]
	v_lshlrev_b32_e32 v34, 16, v129
	v_rsq_f32_e32 v36, v49
	v_cmp_lt_f32_e32 vcc, s74, v49
	v_and_b32_e32 v35, 0xffff0000, v129
	v_and_b32_e32 v31, 0xffff0000, v131
	v_cndmask_b32_e32 v36, v183, v36, vcc
	v_pk_mul_f32 v[38:39], v[46:47], v[36:37] op_sel_hi:[1,0] neg_lo:[0,1] neg_hi:[0,1]
	v_pk_mul_f32 v[36:37], v[44:45], v[36:37] op_sel_hi:[1,0] neg_lo:[0,1] neg_hi:[0,1]
	ds_write_b128 v1, v[36:39] offset:45056
	v_pk_mul_f32 v[38:39], v[38:39], v[42:43] neg_lo:[1,0] neg_hi:[1,0]
	v_rsq_f32_e32 v42, v48
	v_pk_mul_f32 v[36:37], v[36:37], v[40:41] neg_lo:[1,0] neg_hi:[1,0]
	v_cmp_lt_f32_e32 vcc, s74, v48
	ds_write_b128 v1, v[36:39] offset:49152
	v_add_u32_e32 v1, s1, v105
	v_cndmask_b32_e32 v36, v183, v42, vcc
	v_pk_mul_f32 v[38:39], v[58:59], v[36:37] op_sel_hi:[1,0] neg_lo:[0,1] neg_hi:[0,1]
	v_pk_mul_f32 v[36:37], v[56:57], v[36:37] op_sel_hi:[1,0] neg_lo:[0,1] neg_hi:[0,1]
	ds_write_b128 v1, v[36:39] offset:45056
	v_pk_mul_f32 v[38:39], v[38:39], v[54:55] neg_lo:[1,0] neg_hi:[1,0]
	v_pk_mul_f32 v[36:37], v[36:37], v[52:53] neg_lo:[1,0] neg_hi:[1,0]
	ds_write_b128 v1, v[36:39] offset:49152
	v_pk_add_f32 v[36:37], v[54:55], -1.0 op_sel_hi:[1,0]
	v_pk_add_f32 v[38:39], v[52:53], -1.0 op_sel_hi:[1,0]
	v_pk_fma_f32 v[36:37], v[6:7], v[36:37], 1.0 op_sel_hi:[1,1,0]
	v_pk_fma_f32 v[40:41], v[4:5], v[38:39], 1.0 op_sel_hi:[1,1,0]
	v_pk_mul_f32 v[38:39], v[36:37], v[50:51]
	v_pk_mul_f32 v[36:37], v[40:41], v[2:3]
	ds_write_b128 v1, v[36:39] offset:53248
	ds_write_b128 v1, v[32:35] offset:57344
	v_pk_mul_f32 v[218:219], v[32:33], v[36:37]
	v_pk_mul_f32 v[220:221], v[34:35], v[38:39]
	v_pk_mul_f32 v[218:219], v[218:219], v[208:209]
	v_pk_mul_f32 v[220:221], v[220:221], v[210:211]
	v_pk_add_f32 v[218:219], v[218:219], v[220:221]
	s_nop 0
	v_add_f32_e32 v218, v218, v219
	s_nop 1
	v_add_f32_dpp v218, v218, v218 quad_perm:[1,0,3,2] row_mask:0xf bank_mask:0xf
	s_nop 1
	v_add_f32_dpp v218, v218, v218 quad_perm:[2,3,0,1] row_mask:0xf bank_mask:0xf
	s_nop 1
	v_add_f32_dpp v218, v218, v218 row_half_mirror row_mask:0xf bank_mask:0xf
	s_nop 1
	v_add_f32_dpp v218, v218, v218 row_mirror row_mask:0xf bank_mask:0xf
	s_add_i32 s98, s62, 1
	s_lshl_b32 s98, s98, 10
	v_add_co_u32_e32 v216, vcc, s98, v214
	s_nop 1
	v_addc_co_u32_e32 v217, vcc, 0, v215, vcc
	global_store_dword v[216:217], v218, off offset:512
	v_add3_u32 v1, s1, v155, v102
	ds_write_b32 v1, v186 offset:61440
	v_add_u32_e32 v1, s0, v105
	ds_write_b128 v1, v[28:31] offset:31744
